# mixer phase variant: workgroups with bit 3 set run SSD part 1, A pass 1, D first and B last (so the two groups run B at different times)
# speedup vs baseline: 1.0140x; 1.0140x over previous
; #define LAS __attribute__((address_space(3)))
; #define LAUNDER() int tp = TID0(); const int tid = tp, lane = tp & 63, wave = __builtin_amdgcn_readfirstlane(tp >> 6); (void)tid; (void)lane; (void)wave
; __global__ void __launch_bounds__(512) fwd_kernel(Args a) {
;     ...
;             if (EN_B) { LAUNDER(); LAS char* vt = (LAS char*)lds + wave * 16384;
;                 (void)vt; for (int u = blockIdx.x; u < 256; u += G) { mixerB2_unit(u, l, PROJ, YC, a.in[6] + l * 128, a.in[7] + l * 64, KMAX + l * 1024, (LAS char*)lds, tid, wave, lane); } __syncthreads(); }
;             if (EN_S1) { LAUNDER(); __syncthreads();
;                 for (int u = blockIdx.x; u < 256; u += G) ssd_part1_unit(u, PROJ, DT, H, WDT + l * 16384, a.in[11] + l * 8, a.in[8] + l * 5 * 768, a.in[9] + l * 768, a.in[10] + l * 8, STATES, TOT, lds, tid, wave, lane);
.Lmx_b:
	s_cmp_eq_u32 s101, 0
	s_cbranch_scc0 .Lmx_b_go
	s_bitcmp1_b32 s66, 3
	s_cbranch_scc0 .Lmx_b_go
	s_mov_b32 s101, 1
	v_readlane_b32 s0, v253, 56
	v_readlane_b32 s1, v253, 57
	s_nop 1
	v_cndmask_b32_e64 v6, 0, 1, s[0:1]
	s_nop 0
	v_cmp_ne_u32_e64 s[36:37], 1, v6
	s_branch .LBB0_262

; #define LAS __attribute__((address_space(3)))
; #define LAUNDER() int tp = TID0(); const int tid = tp, lane = tp & 63, wave = __builtin_amdgcn_readfirstlane(tp >> 6); (void)tid; (void)lane; (void)wave
; __global__ void __launch_bounds__(512) fwd_kernel(Args a) {
;     ...
;                 (void)vt; for (int u = blockIdx.x; u < 256; u += G) { mixerB2_unit(u, l, PROJ, YC, a.in[6] + l * 128, a.in[7] + l * 64, KMAX + l * 1024, (LAS char*)lds, tid, wave, lane); } __syncthreads(); }
;             if (EN_S1) { LAUNDER(); __syncthreads();
;                 for (int u = blockIdx.x; u < 256; u += G) ssd_part1_unit(u, PROJ, DT, H, WDT + l * 16384, a.in[11] + l * 8, a.in[8] + l * 5 * 768, a.in[9] + l * 768, a.in[10] + l * 8, STATES, TOT, lds, tid, wave, lane);
.LBB0_262:
	s_cmp_eq_u32 s101, 2
	s_cbranch_scc0 .Lmx_s1_go
	s_mov_b32 s101, 0
	v_readlane_b32 s94, v255, 33
	v_readlane_b32 s96, v255, 19
	v_readlane_b32 s95, v255, 34
	v_readlane_b32 s97, v255, 20
	s_waitcnt vmcnt(0)
	s_barrier
	s_branch .LBB0_369
